# one static s_setprio 1 for waves 0-3 of every workgroup, set once in the first in-projection phase (timing only)
# speedup vs baseline: 1.0034x; 1.0022x over previous
; DI int opaque_tid() { int t = threadIdx.x; asm volatile("" : "+v"(t)); return t; }
; DI void inproj_tile(const Params& p, int l, int mt, int nt, char* lds) {
;   const int tid = opaque_tid(), lane = tid & 63, w = tid >> 6, r = lane & 31, h = lane >> 5;
;   const int wm = w & 3, wn = w >> 2;
;   const int m0 = mt * 256;
;   const u16* A = p.Xb + (size_t)m0 * DM;
;   const u16* Bw = p.Wt_in + (size_t)(l & 1) * NIN * DM + (size_t)nt * 128 * DM;
;   if (nt < 42) {
.LBB0_320:
	v_readlane_b32 s0, v240, 17
	v_readlane_b32 s1, v240, 18
	s_andn2_b64 vcc, exec, s[0:1]
	s_lshl_b32 s0, s38, 4
	s_lshl_b32 s50, s38, 3
	v_writelane_b32 v238, s0, 45
	s_nop 1
	v_writelane_b32 v238, s1, 46
	s_cbranch_vccnz .LBB0_370
	s_bitcmp1_b32 s38, 0
	v_readlane_b32 s4, v241, 16
	s_cselect_b32 s0, 0xc00000, 0
	s_add_u32 s18, s4, s0
	v_readlane_b32 s0, v238, 45
	v_readlane_b32 s5, v241, 17
	s_addc_u32 s19, s5, 0
	s_mov_b32 s1, s61
	s_mov_b32 s2, s0
	v_writelane_b32 v238, s2, 45
	s_lshl_b64 s[0:1], s[0:1], 2
	v_readlane_b32 s6, v241, 42
	v_writelane_b32 v238, s3, 46
	v_readlane_b32 s7, v241, 43
	v_readlane_b32 s10, v241, 46
	s_add_u32 s20, s6, s0
	s_addc_u32 s21, s7, s1
	s_lshl_b32 s22, s10, 7
	v_readlane_b32 s23, v238, 17
	v_readfirstlane_b32 s0, v152
	s_nop 3
	s_lshr_b32 s0, s0, 6
	s_cmp_ge_u32 s0, 4
	s_cbranch_scc1 .Lpp_prio
	s_setprio 1
.Lpp_prio:
	v_readlane_b32 s0, v238, 16
	s_and_b32 s41, s0, 7
	s_lshr_b32 s101, s0, 3
	s_cmp_gt_u32 s41, 5
	s_cbranch_scc1 .Lpp_done
